# prompt loop LDS fragment reads issued only two ahead of their MFMA (shallower prefetch, less LDS queueing)
# baseline (speedup 1.0000x reference)
.LBB0_822:
	s_mov_b32 s5, 0
	s_add_i32 s2, s52, 0xfffff000
	buffer_load_dwordx2 v[108:109], v161, s[12:15], s2 offen
	s_add_i32 s3, s53, 0xfe020000
	buffer_load_dwordx4 v[104:107], v150, s[12:15], s3 offen
	s_add_i32 s4, s53, 0xfffe0000
	buffer_load_dwordx4 v[100:103], v150, s[12:15], s4 offen
	ds_read_b64_tr_b16 v[200:201], v162 offset:26624
	ds_read_b64_tr_b16 v[202:203], v162 offset:28160
	ds_read_b64_tr_b16 v[204:205], v162 offset:26688
	ds_read_b64_tr_b16 v[206:207], v162 offset:28224
	v_exp_f32_e32 v184, v84
	v_exp_f32_e32 v216, v36
	v_exp_f32_e32 v185, v85
	v_exp_f32_e32 v217, v37
	s_waitcnt lgkmcnt(2)
	v_mfma_f32_32x32x16_bf16 v[4:19], v[200:203], v[144:147], v[4:19]
	v_add_f32_e32 v224, v184, v216
	v_exp_f32_e32 v186, v86
	v_exp_f32_e32 v218, v38
	v_add_f32_e32 v226, v185, v217
	s_waitcnt lgkmcnt(0)
	v_mfma_f32_32x32x16_bf16 v[20:35], v[204:207], v[144:147], v[20:35]
	ds_read_b64_tr_b16 v[208:209], v162 offset:29696
	ds_read_b64_tr_b16 v[210:211], v162 offset:31232
	v_exp_f32_e32 v187, v87
	v_exp_f32_e32 v219, v39
	v_add_f32_e32 v124, v224, v226
	v_add_f32_e32 v233, v186, v218
	s_waitcnt lgkmcnt(0)
	v_mfma_f32_32x32x16_bf16 v[4:19], v[208:211], v[140:143], v[4:19]
	ds_read_b64_tr_b16 v[212:213], v162 offset:29760
	ds_read_b64_tr_b16 v[214:215], v162 offset:31296
	v_exp_f32_e32 v188, v88
	v_exp_f32_e32 v250, v40
	v_add_f32_e32 v124, v124, v233
	v_add_f32_e32 v224, v187, v219
	s_waitcnt lgkmcnt(0)
	v_mfma_f32_32x32x16_bf16 v[20:35], v[212:215], v[140:143], v[20:35]
	ds_read_b64_tr_b16 v[200:201], v162 offset:32768
	ds_read_b64_tr_b16 v[202:203], v162 offset:34304
	v_exp_f32_e32 v189, v89
	v_exp_f32_e32 v251, v41
	v_add_f32_e32 v124, v124, v224
	v_add_f32_e32 v226, v188, v250
	s_waitcnt lgkmcnt(0)
	v_mfma_f32_32x32x16_bf16 v[4:19], v[200:203], v[136:139], v[4:19]
	ds_read_b64_tr_b16 v[204:205], v162 offset:32832
	ds_read_b64_tr_b16 v[206:207], v162 offset:34368
	v_exp_f32_e32 v190, v90
	v_exp_f32_e32 v252, v42
	v_add_f32_e32 v124, v124, v226
	v_add_f32_e32 v233, v189, v251
	s_waitcnt lgkmcnt(0)
	v_mfma_f32_32x32x16_bf16 v[20:35], v[204:207], v[136:139], v[20:35]
	ds_read_b64_tr_b16 v[208:209], v162 offset:35840
	ds_read_b64_tr_b16 v[210:211], v162 offset:37376
	v_exp_f32_e32 v191, v91
	v_exp_f32_e32 v253, v43
	v_add_f32_e32 v124, v124, v233
	v_add_f32_e32 v224, v190, v252
	s_waitcnt lgkmcnt(0)
	v_mfma_f32_32x32x16_bf16 v[4:19], v[208:211], v[132:135], v[4:19]
	ds_read_b64_tr_b16 v[212:213], v162 offset:35904
	ds_read_b64_tr_b16 v[214:215], v162 offset:37440
	v_exp_f32_e32 v192, v92
	v_exp_f32_e32 v125, v44
	v_add_f32_e32 v124, v124, v224
	v_add_f32_e32 v226, v191, v253
	s_waitcnt lgkmcnt(0)
	v_mfma_f32_32x32x16_bf16 v[20:35], v[212:215], v[132:135], v[20:35]
	ds_read_b128 v[164:167], v156 offset:51200
	ds_read_b128 v[176:179], v155 offset:0
	v_exp_f32_e32 v193, v93
	v_exp_f32_e32 v126, v45
	v_add_f32_e32 v124, v124, v226
	v_add_f32_e32 v233, v192, v125
	s_waitcnt lgkmcnt(0)
	v_mfma_f32_32x32x16_bf16 v[52:67], v[176:179], v[164:167], v[234:249]
	ds_read_b128 v[180:183], v155 offset:6656
	ds_read_b128 v[168:171], v156 offset:51232
	v_exp_f32_e32 v194, v94
	v_exp_f32_e32 v127, v46
	v_add_f32_e32 v124, v124, v233
	v_add_f32_e32 v224, v193, v126
	s_waitcnt lgkmcnt(1)
	v_mfma_f32_32x32x16_bf16 v[68:83], v[180:183], v[164:167], v[234:249]
	ds_read_b128 v[112:115], v155 offset:32
	v_exp_f32_e32 v195, v95
	v_exp_f32_e32 v128, v47
	v_add_f32_e32 v124, v124, v224
	v_add_f32_e32 v226, v194, v127
	s_waitcnt lgkmcnt(0)
	v_mfma_f32_32x32x16_bf16 v[52:67], v[112:115], v[168:171], v[52:67]
	ds_read_b128 v[116:119], v155 offset:6688
	ds_read_b128 v[172:175], v156 offset:51264
	v_exp_f32_e32 v196, v96
	v_exp_f32_e32 v129, v48
	v_add_f32_e32 v124, v124, v226
	v_add_f32_e32 v233, v195, v128
	s_waitcnt lgkmcnt(1)
	v_mfma_f32_32x32x16_bf16 v[68:83], v[116:119], v[168:171], v[68:83]
	ds_read_b128 v[120:123], v155 offset:64
	v_exp_f32_e32 v197, v97
	v_exp_f32_e32 v130, v49
	v_add_f32_e32 v124, v124, v233
	v_add_f32_e32 v224, v196, v129
	s_waitcnt lgkmcnt(0)
	v_mfma_f32_32x32x16_bf16 v[52:67], v[120:123], v[172:175], v[52:67]
	ds_read_b128 v[176:179], v155 offset:6720
	ds_read_b128 v[164:167], v156 offset:51296
	v_exp_f32_e32 v198, v98
	v_exp_f32_e32 v131, v50
	v_add_f32_e32 v124, v124, v224
	v_add_f32_e32 v226, v197, v130
	s_waitcnt lgkmcnt(1)
	v_mfma_f32_32x32x16_bf16 v[68:83], v[176:179], v[172:175], v[68:83]
	ds_read_b128 v[180:183], v155 offset:96
	v_exp_f32_e32 v199, v99
	v_exp_f32_e32 v254, v51
	v_add_f32_e32 v124, v124, v226
	v_add_f32_e32 v233, v198, v131
	s_waitcnt lgkmcnt(0)
	v_mfma_f32_32x32x16_bf16 v[52:67], v[180:183], v[164:167], v[52:67]
	ds_read_b128 v[112:115], v155 offset:6752
	ds_read_b128 v[168:171], v156 offset:51328
	v_add_f32_e32 v124, v124, v233
	v_add_f32_e32 v224, v199, v254
	v_add_f32_e32 v124, v124, v224
	v_cmp_lt_f32_e32 vcc, 0x43800000, v124
	s_cbranch_vccnz .Lpc_s0
.Lpc_b0:
	s_waitcnt lgkmcnt(1)
	v_mfma_f32_32x32x16_bf16 v[68:83], v[112:115], v[164:167], v[68:83]
	ds_read_b128 v[116:119], v155 offset:128
	v_cvt_pk_bf16_f32 v144, v184, v185
	v_cvt_pk_bf16_f32 v145, v186, v187
	v_cvt_pk_bf16_f32 v146, v188, v189
	v_cvt_pk_bf16_f32 v147, v190, v191
	s_waitcnt lgkmcnt(0)
	v_mfma_f32_32x32x16_bf16 v[52:67], v[116:119], v[168:171], v[52:67]
	ds_read_b128 v[120:123], v155 offset:6784
	ds_read_b128 v[172:175], v156 offset:51360
	v_cvt_pk_bf16_f32 v140, v192, v193
	v_cvt_pk_bf16_f32 v141, v194, v195
	v_cvt_pk_bf16_f32 v142, v196, v197
	v_cvt_pk_bf16_f32 v143, v198, v199
	s_waitcnt lgkmcnt(1)
	v_mfma_f32_32x32x16_bf16 v[68:83], v[120:123], v[168:171], v[68:83]
	ds_read_b128 v[176:179], v155 offset:160
	v_cvt_pk_bf16_f32 v136, v216, v217
	v_cvt_pk_bf16_f32 v137, v218, v219
	v_cvt_pk_bf16_f32 v138, v250, v251
	v_cvt_pk_bf16_f32 v139, v252, v253
	s_waitcnt lgkmcnt(0)
	v_mfma_f32_32x32x16_bf16 v[52:67], v[176:179], v[172:175], v[52:67]
	ds_read_b128 v[180:183], v155 offset:6816
	v_cvt_pk_bf16_f32 v132, v125, v126
	v_cvt_pk_bf16_f32 v133, v127, v128
	v_cvt_pk_bf16_f32 v134, v129, v130
	v_cvt_pk_bf16_f32 v135, v131, v254
	s_waitcnt lgkmcnt(0)
	v_mfma_f32_32x32x16_bf16 v[68:83], v[180:183], v[172:175], v[68:83]
	v_add_f32_e32 v152, v152, v124
	s_cmp_eq_u32 s5, 0
	s_cbranch_scc1 .Lpc_nr0
	s_nop 11
	v_pk_mul_f32 v[4:5], v[220:221], v[4:5] op_sel_hi:[0,1]
	v_pk_mul_f32 v[6:7], v[220:221], v[6:7] op_sel_hi:[0,1]
	v_pk_mul_f32 v[8:9], v[220:221], v[8:9] op_sel_hi:[0,1]
	v_pk_mul_f32 v[10:11], v[220:221], v[10:11] op_sel_hi:[0,1]
	v_pk_mul_f32 v[12:13], v[220:221], v[12:13] op_sel_hi:[0,1]
	v_pk_mul_f32 v[14:15], v[220:221], v[14:15] op_sel_hi:[0,1]
	v_pk_mul_f32 v[16:17], v[220:221], v[16:17] op_sel_hi:[0,1]
	v_pk_mul_f32 v[18:19], v[220:221], v[18:19] op_sel_hi:[0,1]
	v_pk_mul_f32 v[20:21], v[220:221], v[20:21] op_sel_hi:[0,1]
	v_pk_mul_f32 v[22:23], v[220:221], v[22:23] op_sel_hi:[0,1]
	v_pk_mul_f32 v[24:25], v[220:221], v[24:25] op_sel_hi:[0,1]
	v_pk_mul_f32 v[26:27], v[220:221], v[26:27] op_sel_hi:[0,1]
	v_pk_mul_f32 v[28:29], v[220:221], v[28:29] op_sel_hi:[0,1]
	v_pk_mul_f32 v[30:31], v[220:221], v[30:31] op_sel_hi:[0,1]
	v_pk_mul_f32 v[32:33], v[220:221], v[32:33] op_sel_hi:[0,1]
	v_pk_mul_f32 v[34:35], v[220:221], v[34:35] op_sel_hi:[0,1]
	v_sub_f32_e32 v52, v52, v222
	v_sub_f32_e32 v68, v68, v222
	v_sub_f32_e32 v53, v53, v222
	v_sub_f32_e32 v69, v69, v222
	v_sub_f32_e32 v54, v54, v222
	v_sub_f32_e32 v70, v70, v222
	v_sub_f32_e32 v55, v55, v222
	v_sub_f32_e32 v71, v71, v222
	v_sub_f32_e32 v56, v56, v222
	v_sub_f32_e32 v72, v72, v222
	v_sub_f32_e32 v57, v57, v222
	v_sub_f32_e32 v73, v73, v222
	v_sub_f32_e32 v58, v58, v222
	v_sub_f32_e32 v74, v74, v222
	v_sub_f32_e32 v59, v59, v222
	v_sub_f32_e32 v75, v75, v222
	v_sub_f32_e32 v60, v60, v222
	v_sub_f32_e32 v76, v76, v222
	v_sub_f32_e32 v61, v61, v222
	v_sub_f32_e32 v77, v77, v222
	v_sub_f32_e32 v62, v62, v222
	v_sub_f32_e32 v78, v78, v222
	v_sub_f32_e32 v63, v63, v222
	v_sub_f32_e32 v79, v79, v222
	v_sub_f32_e32 v64, v64, v222
	v_sub_f32_e32 v80, v80, v222
	v_sub_f32_e32 v65, v65, v222
	v_sub_f32_e32 v81, v81, v222
	v_sub_f32_e32 v66, v66, v222
	v_sub_f32_e32 v82, v82, v222
	v_sub_f32_e32 v67, v67, v222
	v_sub_f32_e32 v83, v83, v222
	v_sub_f32_e32 v234, v234, v222
	v_sub_f32_e32 v235, v235, v222
	v_sub_f32_e32 v236, v236, v222
	v_sub_f32_e32 v237, v237, v222
	v_sub_f32_e32 v238, v238, v222
	v_sub_f32_e32 v239, v239, v222
	v_sub_f32_e32 v240, v240, v222
	v_sub_f32_e32 v241, v241, v222
	v_sub_f32_e32 v242, v242, v222
	v_sub_f32_e32 v243, v243, v222
	v_sub_f32_e32 v244, v244, v222
	v_sub_f32_e32 v245, v245, v222
	v_sub_f32_e32 v246, v246, v222
	v_sub_f32_e32 v247, v247, v222
	v_sub_f32_e32 v248, v248, v222
	v_sub_f32_e32 v249, v249, v222
.Lpc_nr0:
	s_waitcnt vmcnt(1)
	ds_write_b128 v157, v[104:107] offset:13312
	ds_write_b64 v158, v[108:109] offset:13440
	s_waitcnt vmcnt(0)
	ds_write_b128 v151, v[100:103] offset:38912
	s_waitcnt lgkmcnt(0)
	s_barrier
	s_mov_b32 s5, 0
	buffer_load_dwordx2 v[108:109], v161, s[12:15], s52 offen
	s_add_i32 s3, s53, 0xfe040000
	buffer_load_dwordx4 v[104:107], v150, s[12:15], s3 offen
	buffer_load_dwordx4 v[100:103], v150, s[12:15], s53 offen
	ds_read_b64_tr_b16 v[200:201], v162 offset:38912
	ds_read_b64_tr_b16 v[202:203], v162 offset:40448
	ds_read_b64_tr_b16 v[204:205], v162 offset:38976
	ds_read_b64_tr_b16 v[206:207], v162 offset:40512
	v_exp_f32_e32 v184, v52
	v_exp_f32_e32 v216, v68
	v_exp_f32_e32 v185, v53
	v_exp_f32_e32 v217, v69
	s_waitcnt lgkmcnt(2)
	v_mfma_f32_32x32x16_bf16 v[4:19], v[200:203], v[144:147], v[4:19]
	v_add_f32_e32 v224, v184, v216
	v_exp_f32_e32 v186, v54
	v_exp_f32_e32 v218, v70
	v_add_f32_e32 v226, v185, v217
	s_waitcnt lgkmcnt(0)
	v_mfma_f32_32x32x16_bf16 v[20:35], v[204:207], v[144:147], v[20:35]
	ds_read_b64_tr_b16 v[208:209], v162 offset:41984
	ds_read_b64_tr_b16 v[210:211], v162 offset:43520
	v_exp_f32_e32 v187, v55
	v_exp_f32_e32 v219, v71
	v_add_f32_e32 v124, v224, v226
	v_add_f32_e32 v233, v186, v218
	s_waitcnt lgkmcnt(0)
	v_mfma_f32_32x32x16_bf16 v[4:19], v[208:211], v[140:143], v[4:19]
	ds_read_b64_tr_b16 v[212:213], v162 offset:42048
	ds_read_b64_tr_b16 v[214:215], v162 offset:43584
	v_exp_f32_e32 v188, v56
	v_exp_f32_e32 v250, v72
	v_add_f32_e32 v124, v124, v233
	v_add_f32_e32 v224, v187, v219
	s_waitcnt lgkmcnt(0)
	v_mfma_f32_32x32x16_bf16 v[20:35], v[212:215], v[140:143], v[20:35]
	ds_read_b64_tr_b16 v[200:201], v162 offset:45056
	ds_read_b64_tr_b16 v[202:203], v162 offset:46592
	v_exp_f32_e32 v189, v57
	v_exp_f32_e32 v251, v73
	v_add_f32_e32 v124, v124, v224
	v_add_f32_e32 v226, v188, v250
	s_waitcnt lgkmcnt(0)
	v_mfma_f32_32x32x16_bf16 v[4:19], v[200:203], v[136:139], v[4:19]
	ds_read_b64_tr_b16 v[204:205], v162 offset:45120
	ds_read_b64_tr_b16 v[206:207], v162 offset:46656
	v_exp_f32_e32 v190, v58
	v_exp_f32_e32 v252, v74
	v_add_f32_e32 v124, v124, v226
	v_add_f32_e32 v233, v189, v251
	s_waitcnt lgkmcnt(0)
	v_mfma_f32_32x32x16_bf16 v[20:35], v[204:207], v[136:139], v[20:35]
	ds_read_b64_tr_b16 v[208:209], v162 offset:48128
	ds_read_b64_tr_b16 v[210:211], v162 offset:49664
	v_exp_f32_e32 v191, v59
	v_exp_f32_e32 v253, v75
	v_add_f32_e32 v124, v124, v233
	v_add_f32_e32 v224, v190, v252
	s_waitcnt lgkmcnt(0)
	v_mfma_f32_32x32x16_bf16 v[4:19], v[208:211], v[132:135], v[4:19]
	ds_read_b64_tr_b16 v[212:213], v162 offset:48192
	ds_read_b64_tr_b16 v[214:215], v162 offset:49728
	v_exp_f32_e32 v192, v60
	v_exp_f32_e32 v125, v76
	v_add_f32_e32 v124, v124, v224
	v_add_f32_e32 v226, v191, v253
	s_waitcnt lgkmcnt(0)
	v_mfma_f32_32x32x16_bf16 v[20:35], v[212:215], v[132:135], v[20:35]
	ds_read_b128 v[164:167], v156 offset:51200
	ds_read_b128 v[176:179], v155 offset:13312
	v_exp_f32_e32 v193, v61
	v_exp_f32_e32 v126, v77
	v_add_f32_e32 v124, v124, v226
	v_add_f32_e32 v233, v192, v125
	s_waitcnt lgkmcnt(0)
	v_mfma_f32_32x32x16_bf16 v[84:99], v[176:179], v[164:167], v[234:249]
	ds_read_b128 v[180:183], v155 offset:19968
	ds_read_b128 v[168:171], v156 offset:51232
	v_exp_f32_e32 v194, v62
	v_exp_f32_e32 v127, v78
	v_add_f32_e32 v124, v124, v233
	v_add_f32_e32 v224, v193, v126
	s_waitcnt lgkmcnt(1)
	v_mfma_f32_32x32x16_bf16 v[36:51], v[180:183], v[164:167], v[234:249]
	ds_read_b128 v[112:115], v155 offset:13344
	v_exp_f32_e32 v195, v63
	v_exp_f32_e32 v128, v79
	v_add_f32_e32 v124, v124, v224
	v_add_f32_e32 v226, v194, v127
	s_waitcnt lgkmcnt(0)
	v_mfma_f32_32x32x16_bf16 v[84:99], v[112:115], v[168:171], v[84:99]
	ds_read_b128 v[116:119], v155 offset:20000
	ds_read_b128 v[172:175], v156 offset:51264
	v_exp_f32_e32 v196, v64
	v_exp_f32_e32 v129, v80
	v_add_f32_e32 v124, v124, v226
	v_add_f32_e32 v233, v195, v128
	s_waitcnt lgkmcnt(1)
	v_mfma_f32_32x32x16_bf16 v[36:51], v[116:119], v[168:171], v[36:51]
	ds_read_b128 v[120:123], v155 offset:13376
	v_exp_f32_e32 v197, v65
	v_exp_f32_e32 v130, v81
	v_add_f32_e32 v124, v124, v233
	v_add_f32_e32 v224, v196, v129
	s_waitcnt lgkmcnt(0)
	v_mfma_f32_32x32x16_bf16 v[84:99], v[120:123], v[172:175], v[84:99]
	ds_read_b128 v[176:179], v155 offset:20032
	ds_read_b128 v[164:167], v156 offset:51296
	v_exp_f32_e32 v198, v66
	v_exp_f32_e32 v131, v82
	v_add_f32_e32 v124, v124, v224
	v_add_f32_e32 v226, v197, v130
	s_waitcnt lgkmcnt(1)
	v_mfma_f32_32x32x16_bf16 v[36:51], v[176:179], v[172:175], v[36:51]
	ds_read_b128 v[180:183], v155 offset:13408
	v_exp_f32_e32 v199, v67
	v_exp_f32_e32 v254, v83
	v_add_f32_e32 v124, v124, v226
	v_add_f32_e32 v233, v198, v131
	s_waitcnt lgkmcnt(0)
	v_mfma_f32_32x32x16_bf16 v[84:99], v[180:183], v[164:167], v[84:99]
	ds_read_b128 v[112:115], v155 offset:20064
	ds_read_b128 v[168:171], v156 offset:51328
	v_add_f32_e32 v124, v124, v233
	v_add_f32_e32 v224, v199, v254
	v_add_f32_e32 v124, v124, v224
	v_cmp_lt_f32_e32 vcc, 0x43800000, v124
	s_cbranch_vccnz .Lpc_s1
.Lpc_b1:
	s_waitcnt lgkmcnt(1)
	v_mfma_f32_32x32x16_bf16 v[36:51], v[112:115], v[164:167], v[36:51]
	ds_read_b128 v[116:119], v155 offset:13440
	v_cvt_pk_bf16_f32 v144, v184, v185
	v_cvt_pk_bf16_f32 v145, v186, v187
	v_cvt_pk_bf16_f32 v146, v188, v189
	v_cvt_pk_bf16_f32 v147, v190, v191
	s_waitcnt lgkmcnt(0)
	v_mfma_f32_32x32x16_bf16 v[84:99], v[116:119], v[168:171], v[84:99]
	ds_read_b128 v[120:123], v155 offset:20096
	ds_read_b128 v[172:175], v156 offset:51360
	v_cvt_pk_bf16_f32 v140, v192, v193
	v_cvt_pk_bf16_f32 v141, v194, v195
	v_cvt_pk_bf16_f32 v142, v196, v197
	v_cvt_pk_bf16_f32 v143, v198, v199
	s_waitcnt lgkmcnt(1)
	v_mfma_f32_32x32x16_bf16 v[36:51], v[120:123], v[168:171], v[36:51]
	ds_read_b128 v[176:179], v155 offset:13472
	v_cvt_pk_bf16_f32 v136, v216, v217
	v_cvt_pk_bf16_f32 v137, v218, v219
	v_cvt_pk_bf16_f32 v138, v250, v251
	v_cvt_pk_bf16_f32 v139, v252, v253
	s_waitcnt lgkmcnt(0)
	v_mfma_f32_32x32x16_bf16 v[84:99], v[176:179], v[172:175], v[84:99]
	ds_read_b128 v[180:183], v155 offset:20128
	v_cvt_pk_bf16_f32 v132, v125, v126
	v_cvt_pk_bf16_f32 v133, v127, v128
	v_cvt_pk_bf16_f32 v134, v129, v130
	v_cvt_pk_bf16_f32 v135, v131, v254
	s_waitcnt lgkmcnt(0)
	v_mfma_f32_32x32x16_bf16 v[36:51], v[180:183], v[172:175], v[36:51]
	v_add_f32_e32 v152, v152, v124
	s_cmp_eq_u32 s5, 0
	s_cbranch_scc1 .Lpc_nr1
	s_nop 11
	v_pk_mul_f32 v[4:5], v[220:221], v[4:5] op_sel_hi:[0,1]
	v_pk_mul_f32 v[6:7], v[220:221], v[6:7] op_sel_hi:[0,1]
	v_pk_mul_f32 v[8:9], v[220:221], v[8:9] op_sel_hi:[0,1]
	v_pk_mul_f32 v[10:11], v[220:221], v[10:11] op_sel_hi:[0,1]
	v_pk_mul_f32 v[12:13], v[220:221], v[12:13] op_sel_hi:[0,1]
	v_pk_mul_f32 v[14:15], v[220:221], v[14:15] op_sel_hi:[0,1]
	v_pk_mul_f32 v[16:17], v[220:221], v[16:17] op_sel_hi:[0,1]
	v_pk_mul_f32 v[18:19], v[220:221], v[18:19] op_sel_hi:[0,1]
	v_pk_mul_f32 v[20:21], v[220:221], v[20:21] op_sel_hi:[0,1]
	v_pk_mul_f32 v[22:23], v[220:221], v[22:23] op_sel_hi:[0,1]
	v_pk_mul_f32 v[24:25], v[220:221], v[24:25] op_sel_hi:[0,1]
	v_pk_mul_f32 v[26:27], v[220:221], v[26:27] op_sel_hi:[0,1]
	v_pk_mul_f32 v[28:29], v[220:221], v[28:29] op_sel_hi:[0,1]
	v_pk_mul_f32 v[30:31], v[220:221], v[30:31] op_sel_hi:[0,1]
	v_pk_mul_f32 v[32:33], v[220:221], v[32:33] op_sel_hi:[0,1]
	v_pk_mul_f32 v[34:35], v[220:221], v[34:35] op_sel_hi:[0,1]
	v_sub_f32_e32 v84, v84, v222
	v_sub_f32_e32 v36, v36, v222
	v_sub_f32_e32 v85, v85, v222
	v_sub_f32_e32 v37, v37, v222
	v_sub_f32_e32 v86, v86, v222
	v_sub_f32_e32 v38, v38, v222
	v_sub_f32_e32 v87, v87, v222
	v_sub_f32_e32 v39, v39, v222
	v_sub_f32_e32 v88, v88, v222
	v_sub_f32_e32 v40, v40, v222
	v_sub_f32_e32 v89, v89, v222
	v_sub_f32_e32 v41, v41, v222
	v_sub_f32_e32 v90, v90, v222
	v_sub_f32_e32 v42, v42, v222
	v_sub_f32_e32 v91, v91, v222
	v_sub_f32_e32 v43, v43, v222
	v_sub_f32_e32 v92, v92, v222
	v_sub_f32_e32 v44, v44, v222
	v_sub_f32_e32 v93, v93, v222
	v_sub_f32_e32 v45, v45, v222
	v_sub_f32_e32 v94, v94, v222
	v_sub_f32_e32 v46, v46, v222
	v_sub_f32_e32 v95, v95, v222
	v_sub_f32_e32 v47, v47, v222
	v_sub_f32_e32 v96, v96, v222
	v_sub_f32_e32 v48, v48, v222
	v_sub_f32_e32 v97, v97, v222
	v_sub_f32_e32 v49, v49, v222
	v_sub_f32_e32 v98, v98, v222
	v_sub_f32_e32 v50, v50, v222
	v_sub_f32_e32 v99, v99, v222
	v_sub_f32_e32 v51, v51, v222
	v_sub_f32_e32 v234, v234, v222
	v_sub_f32_e32 v235, v235, v222
	v_sub_f32_e32 v236, v236, v222
	v_sub_f32_e32 v237, v237, v222
	v_sub_f32_e32 v238, v238, v222
	v_sub_f32_e32 v239, v239, v222
	v_sub_f32_e32 v240, v240, v222
	v_sub_f32_e32 v241, v241, v222
	v_sub_f32_e32 v242, v242, v222
	v_sub_f32_e32 v243, v243, v222
	v_sub_f32_e32 v244, v244, v222
	v_sub_f32_e32 v245, v245, v222
	v_sub_f32_e32 v246, v246, v222
	v_sub_f32_e32 v247, v247, v222
	v_sub_f32_e32 v248, v248, v222
	v_sub_f32_e32 v249, v249, v222
